# resid epilogue pass 2: the 8 per-group rss loads issued together into free VGPRs, per-group vmcnt(0) waits removed
# speedup vs baseline: 1.0007x; 1.0007x over previous
; __device__ __forceinline__ unsigned pk2(float lo, float hi) { return pg8::cvt_pk_bf16(lo, hi); }
;     __device__ __forceinline__ void operator()(const f32x4 (&acc_)[2][2][4][2], const pg8::Unit& u, int wr, int wc, int fr, int fq) const {
;     ...
;             const float* ng = ap->in[I_NORMG] + (size_t)((nl & 1) * 3 + nn) * DM + col0;
;             const float* nsc = mod + (size_t)(nl & 1) * 8 * NMODV + (size_t)b * NMODV + (size_t)(3 * nn + 1) * DM + col0;
;             const float* nsh = mod + (size_t)(nl & 1) * 8 * NMODV + (size_t)b * NMODV + (size_t)(3 * nn) * DM + col0;
;             f32x4 gs[2][2], sh[2][2];
; #pragma unroll
;             for (int bj = 0; bj < 2; ++bj)
; #pragma unroll
;                 for (int n = 0; n < 2; ++n) { gs[bj][n] = *(const f32x4*)(ng + bj * 128 + n * 16) * (*(const f32x4*)(nsc + bj * 128 + n * 16) + 1.f); sh[bj][n] = *(const f32x4*)(nsh + bj * 128 + n * 16); }
; #pragma unroll
;             for (int ai = 0; ai < 2; ++ai)
; #pragma unroll
;                 for (int m = 0; m < 4; ++m) {
;                     const int row = row0 + ai * 128 + m * 16;
;                     const float rs = rsqrtf(__hip_atomic_load(rss + row, __ATOMIC_RELAXED, __HIP_MEMORY_SCOPE_AGENT) * (1.f / DM) + EPSN);
;                     const size_t off = (size_t)row * DM + col0;
; #pragma unroll
;                     for (int bj = 0; bj < 2; ++bj)
; #pragma unroll
;                         for (int n = 0; n < 2; ++n) { const f32x4 y = acc[ai][bj][m][n] * rs * gs[bj][n] + sh[bj][n];
;                             *(u32x2*)(xb + off + bj * 128 + n * 16) = (u32x2){pk2(y.x, y.y), pk2(y.z, y.w)}; }
;                 }
.LBB0_453:
	v_readlane_b32 s58, v255, 7
	v_readlane_b32 s59, v255, 8
	s_load_dwordx2 s[58:59], s[58:59], 0x20
	v_readlane_b32 s31, v255, 37
	v_lshlrev_b64 v[64:65], 2, v[178:179]
	s_waitcnt lgkmcnt(0)
	s_add_u32 s58, s58, s31
	s_addc_u32 s59, s59, 0
	v_readlane_b32 s31, v255, 39
	v_lshl_add_u64 v[164:165], s[58:59], 0, v[64:65]
	s_add_u32 s58, s31, s66
	v_readlane_b32 s31, v255, 40
	s_addc_u32 s59, s31, s67
	v_lshl_add_u64 v[182:183], s[58:59], 0, v[64:65]
	s_movk_i32 s31, 0x1000
	v_add_co_u32_e32 v68, vcc, s31, v182
	global_load_dwordx4 v[64:67], v[164:165], off
	s_nop 0
	v_addc_co_u32_e32 v69, vcc, 0, v183, vcc
	global_load_dwordx4 v[68:71], v[68:69], off
	s_mov_b64 s[58:59], 0x1000
	v_lshl_add_u64 v[166:167], v[182:183], 0, s[58:59]
	v_readlane_b32 s58, v255, 30
	v_readlane_b32 s59, v255, 31
	s_waitcnt vmcnt(0)
	v_pk_add_f32 v[70:71], v[70:71], 1.0 op_sel_hi:[1,0]
	v_pk_add_f32 v[68:69], v[68:69], 1.0 op_sel_hi:[1,0]
	v_pk_mul_f32 v[160:161], v[66:67], v[70:71]
	v_pk_mul_f32 v[162:163], v[64:65], v[68:69]
	global_load_dwordx4 v[64:67], v[182:183], off
	global_load_dwordx4 v[68:71], v[164:165], off offset:64
	global_load_dwordx4 v[72:75], v[166:167], off offset:64
	v_lshl_add_u64 v[178:179], v[178:179], 1, s[58:59]
	s_waitcnt vmcnt(0)
	v_pk_add_f32 v[74:75], v[74:75], 1.0 op_sel_hi:[1,0]
	v_pk_add_f32 v[72:73], v[72:73], 1.0 op_sel_hi:[1,0]
	v_pk_mul_f32 v[168:169], v[70:71], v[74:75]
	v_pk_mul_f32 v[170:171], v[68:69], v[72:73]
	global_load_dwordx4 v[68:71], v[182:183], off offset:64
	global_load_dwordx4 v[72:75], v[164:165], off offset:512
	global_load_dwordx4 v[80:83], v[166:167], off offset:512
	s_waitcnt vmcnt(0)
	v_pk_add_f32 v[82:83], v[82:83], 1.0 op_sel_hi:[1,0]
	v_pk_add_f32 v[80:81], v[80:81], 1.0 op_sel_hi:[1,0]
	v_pk_mul_f32 v[172:173], v[74:75], v[82:83]
	v_pk_mul_f32 v[174:175], v[72:73], v[80:81]
	global_load_dwordx4 v[72:75], v[182:183], off offset:512
	global_load_dwordx4 v[80:83], v[164:165], off offset:576
	s_nop 0
	global_load_dwordx4 v[164:167], v[166:167], off offset:576
	s_waitcnt vmcnt(0)
	v_pk_add_f32 v[166:167], v[166:167], 1.0 op_sel_hi:[1,0]
	v_pk_add_f32 v[184:185], v[164:165], 1.0 op_sel_hi:[1,0]
	v_pk_mul_f32 v[164:165], v[82:83], v[166:167]
	v_pk_mul_f32 v[166:167], v[80:81], v[184:185]
	global_load_dwordx4 v[80:83], v[182:183], off offset:576
	global_load_dword v147, v[150:151], off sc1
	global_load_dword v216, v[150:151], off offset:64 sc1
	global_load_dword v217, v[150:151], off offset:128 sc1
	global_load_dword v218, v[150:151], off offset:192 sc1
	global_load_dword v219, v[150:151], off offset:512 sc1
	global_load_dword v220, v[150:151], off offset:576 sc1
	global_load_dword v221, v[150:151], off offset:640 sc1
	global_load_dword v222, v[150:151], off offset:704 sc1
	v_lshlrev_b64 v[184:185], 11, v[194:195]
	v_lshl_add_u64 v[194:195], v[178:179], 0, v[184:185]
	s_waitcnt vmcnt(0)
	v_fmamk_f32 v147, v147, 0x3a800000, v197
	v_cmp_gt_f32_e32 vcc, s78, v147
	v_mul_f32_e32 v182, 0x4b800000, v147
	s_nop 0
	v_cndmask_b32_e32 v147, v147, v182, vcc
	v_rsq_f32_e32 v147, v147
	s_nop 0
	v_mul_f32_e32 v182, 0x45800000, v147
	v_cndmask_b32_e32 v182, v147, v182, vcc
	v_pk_mul_f32 v[140:141], v[140:141], v[182:183] op_sel_hi:[1,0]
	v_pk_mul_f32 v[136:137], v[136:137], v[182:183] op_sel_hi:[1,0]
	v_pk_mul_f32 v[132:133], v[132:133], v[182:183] op_sel_hi:[1,0]
	v_pk_mul_f32 v[128:129], v[128:129], v[182:183] op_sel_hi:[1,0]
	v_pk_mul_f32 v[142:143], v[142:143], v[182:183] op_sel_hi:[1,0]
	v_pk_fma_f32 v[140:141], v[162:163], v[140:141], v[64:65]
	v_pk_mul_f32 v[138:139], v[138:139], v[182:183] op_sel_hi:[1,0]
	v_pk_fma_f32 v[136:137], v[170:171], v[136:137], v[68:69]
	v_pk_mul_f32 v[134:135], v[134:135], v[182:183] op_sel_hi:[1,0]
	v_pk_fma_f32 v[132:133], v[174:175], v[132:133], v[72:73]
	v_pk_mul_f32 v[130:131], v[130:131], v[182:183] op_sel_hi:[1,0]
	v_pk_fma_f32 v[128:129], v[166:167], v[128:129], v[80:81]
	v_pk_fma_f32 v[142:143], v[160:161], v[142:143], v[66:67]
	v_cvt_pk_bf16_f32 v140, v140, v141
	v_pk_fma_f32 v[138:139], v[168:169], v[138:139], v[70:71]
	v_cvt_pk_bf16_f32 v141, v142, v143
	global_store_dwordx2 v[194:195], v[140:141], off
	v_cvt_pk_bf16_f32 v136, v136, v137
	v_cvt_pk_bf16_f32 v137, v138, v139
	global_store_dwordx2 v[194:195], v[136:137], off offset:32
	v_pk_fma_f32 v[134:135], v[172:173], v[134:135], v[74:75]
	v_cvt_pk_bf16_f32 v132, v132, v133
	v_pk_fma_f32 v[130:131], v[164:165], v[130:131], v[82:83]
	v_cvt_pk_bf16_f32 v133, v134, v135
	global_store_dwordx2 v[194:195], v[132:133], off offset:256
	v_cvt_pk_bf16_f32 v128, v128, v129
	v_cvt_pk_bf16_f32 v129, v130, v131
	global_store_dwordx2 v[194:195], v[128:129], off offset:288
	v_mov_b32_e32 v128, v216
	v_lshlrev_b64 v[130:131], 11, v[192:193]
	v_lshl_add_u64 v[130:131], v[178:179], 0, v[130:131]
	v_fmamk_f32 v128, v128, 0x3a800000, v197
	v_cmp_gt_f32_e32 vcc, s78, v128
	v_mul_f32_e32 v129, 0x4b800000, v128
	s_nop 0
	v_cndmask_b32_e32 v128, v128, v129, vcc
	v_rsq_f32_e32 v128, v128
	s_nop 0
	v_mul_f32_e32 v129, 0x45800000, v128
	v_cndmask_b32_e32 v128, v128, v129, vcc
	v_pk_mul_f32 v[124:125], v[124:125], v[128:129] op_sel_hi:[1,0]
	v_pk_mul_f32 v[120:121], v[120:121], v[128:129] op_sel_hi:[1,0]
	v_pk_mul_f32 v[116:117], v[116:117], v[128:129] op_sel_hi:[1,0]
	v_pk_mul_f32 v[112:113], v[112:113], v[128:129] op_sel_hi:[1,0]
	v_pk_mul_f32 v[126:127], v[126:127], v[128:129] op_sel_hi:[1,0]
	v_pk_fma_f32 v[124:125], v[162:163], v[124:125], v[64:65]
	v_pk_mul_f32 v[122:123], v[122:123], v[128:129] op_sel_hi:[1,0]
	v_pk_fma_f32 v[120:121], v[170:171], v[120:121], v[68:69]
	v_pk_mul_f32 v[118:119], v[118:119], v[128:129] op_sel_hi:[1,0]
; __device__ __forceinline__ unsigned pk2(float lo, float hi) { return pg8::cvt_pk_bf16(lo, hi); }
;     __device__ __forceinline__ void operator()(const f32x4 (&acc_)[2][2][4][2], const pg8::Unit& u, int wr, int wc, int fr, int fq) const {
;     ...
;             for (int ai = 0; ai < 2; ++ai)
; #pragma unroll
;                 for (int m = 0; m < 4; ++m) {
;                     const int row = row0 + ai * 128 + m * 16;
;                     const float rs = rsqrtf(__hip_atomic_load(rss + row, __ATOMIC_RELAXED, __HIP_MEMORY_SCOPE_AGENT) * (1.f / DM) + EPSN);
;                     const size_t off = (size_t)row * DM + col0;
; #pragma unroll
;                     for (int bj = 0; bj < 2; ++bj)
; #pragma unroll
;                         for (int n = 0; n < 2; ++n) { const f32x4 y = acc[ai][bj][m][n] * rs * gs[bj][n] + sh[bj][n];
;                             *(u32x2*)(xb + off + bj * 128 + n * 16) = (u32x2){pk2(y.x, y.y), pk2(y.z, y.w)}; }
;                 }
	v_pk_fma_f32 v[116:117], v[174:175], v[116:117], v[72:73]
	v_pk_mul_f32 v[114:115], v[114:115], v[128:129] op_sel_hi:[1,0]
	v_pk_fma_f32 v[112:113], v[166:167], v[112:113], v[80:81]
	v_pk_fma_f32 v[126:127], v[160:161], v[126:127], v[66:67]
	v_cvt_pk_bf16_f32 v124, v124, v125
	v_pk_fma_f32 v[122:123], v[168:169], v[122:123], v[70:71]
	v_cvt_pk_bf16_f32 v125, v126, v127
	global_store_dwordx2 v[130:131], v[124:125], off
	v_cvt_pk_bf16_f32 v120, v120, v121
	v_cvt_pk_bf16_f32 v121, v122, v123
	global_store_dwordx2 v[130:131], v[120:121], off offset:32
	v_pk_fma_f32 v[118:119], v[172:173], v[118:119], v[74:75]
	v_cvt_pk_bf16_f32 v116, v116, v117
	v_pk_fma_f32 v[114:115], v[164:165], v[114:115], v[82:83]
	v_cvt_pk_bf16_f32 v117, v118, v119
	global_store_dwordx2 v[130:131], v[116:117], off offset:256
	v_cvt_pk_bf16_f32 v112, v112, v113
	v_cvt_pk_bf16_f32 v113, v114, v115
	global_store_dwordx2 v[130:131], v[112:113], off offset:288
	v_mov_b32_e32 v112, v217
	v_lshlrev_b64 v[114:115], 11, v[180:181]
	v_lshl_add_u64 v[114:115], v[178:179], 0, v[114:115]
	v_fmamk_f32 v112, v112, 0x3a800000, v197
	v_cmp_gt_f32_e32 vcc, s78, v112
	v_mul_f32_e32 v113, 0x4b800000, v112
	s_nop 0
	v_cndmask_b32_e32 v112, v112, v113, vcc
	v_rsq_f32_e32 v112, v112
	s_nop 0
	v_mul_f32_e32 v113, 0x45800000, v112
	v_cndmask_b32_e32 v112, v112, v113, vcc
	v_pk_mul_f32 v[108:109], v[108:109], v[112:113] op_sel_hi:[1,0]
	v_pk_mul_f32 v[104:105], v[104:105], v[112:113] op_sel_hi:[1,0]
	v_pk_mul_f32 v[100:101], v[100:101], v[112:113] op_sel_hi:[1,0]
	v_pk_mul_f32 v[96:97], v[96:97], v[112:113] op_sel_hi:[1,0]
	v_pk_mul_f32 v[110:111], v[110:111], v[112:113] op_sel_hi:[1,0]
	v_pk_fma_f32 v[108:109], v[162:163], v[108:109], v[64:65]
	v_pk_mul_f32 v[106:107], v[106:107], v[112:113] op_sel_hi:[1,0]
	v_pk_fma_f32 v[104:105], v[170:171], v[104:105], v[68:69]
	v_pk_mul_f32 v[102:103], v[102:103], v[112:113] op_sel_hi:[1,0]
	v_pk_fma_f32 v[100:101], v[174:175], v[100:101], v[72:73]
	v_pk_mul_f32 v[98:99], v[98:99], v[112:113] op_sel_hi:[1,0]
	v_pk_fma_f32 v[96:97], v[166:167], v[96:97], v[80:81]
	v_pk_fma_f32 v[110:111], v[160:161], v[110:111], v[66:67]
	v_cvt_pk_bf16_f32 v108, v108, v109
	v_pk_fma_f32 v[106:107], v[168:169], v[106:107], v[70:71]
	v_cvt_pk_bf16_f32 v109, v110, v111
	global_store_dwordx2 v[114:115], v[108:109], off
	v_cvt_pk_bf16_f32 v104, v104, v105
	v_cvt_pk_bf16_f32 v105, v106, v107
	global_store_dwordx2 v[114:115], v[104:105], off offset:32
	v_pk_fma_f32 v[102:103], v[172:173], v[102:103], v[74:75]
	v_cvt_pk_bf16_f32 v100, v100, v101
	v_pk_fma_f32 v[98:99], v[164:165], v[98:99], v[82:83]
	v_cvt_pk_bf16_f32 v101, v102, v103
	global_store_dwordx2 v[114:115], v[100:101], off offset:256
	v_cvt_pk_bf16_f32 v96, v96, v97
	v_cvt_pk_bf16_f32 v97, v98, v99
	global_store_dwordx2 v[114:115], v[96:97], off offset:288
	v_mov_b32_e32 v96, v218
	v_lshlrev_b64 v[98:99], 11, v[176:177]
	v_lshl_add_u64 v[98:99], v[178:179], 0, v[98:99]
	v_fmamk_f32 v96, v96, 0x3a800000, v197
	v_cmp_gt_f32_e32 vcc, s78, v96
	v_mul_f32_e32 v97, 0x4b800000, v96
	s_nop 0
	v_cndmask_b32_e32 v96, v96, v97, vcc
	v_rsq_f32_e32 v96, v96
	s_nop 0
	v_mul_f32_e32 v97, 0x45800000, v96
	v_cndmask_b32_e32 v96, v96, v97, vcc
	v_pk_mul_f32 v[92:93], v[92:93], v[96:97] op_sel_hi:[1,0]
	v_pk_mul_f32 v[88:89], v[88:89], v[96:97] op_sel_hi:[1,0]
	v_pk_mul_f32 v[84:85], v[84:85], v[96:97] op_sel_hi:[1,0]
	v_pk_mul_f32 v[76:77], v[76:77], v[96:97] op_sel_hi:[1,0]
	v_pk_mul_f32 v[94:95], v[94:95], v[96:97] op_sel_hi:[1,0]
	v_pk_fma_f32 v[92:93], v[162:163], v[92:93], v[64:65]
	v_pk_mul_f32 v[90:91], v[90:91], v[96:97] op_sel_hi:[1,0]
	v_pk_fma_f32 v[88:89], v[170:171], v[88:89], v[68:69]
	v_pk_mul_f32 v[86:87], v[86:87], v[96:97] op_sel_hi:[1,0]
	v_pk_fma_f32 v[84:85], v[174:175], v[84:85], v[72:73]
	v_pk_mul_f32 v[78:79], v[78:79], v[96:97] op_sel_hi:[1,0]
	v_pk_fma_f32 v[76:77], v[166:167], v[76:77], v[80:81]
	v_pk_fma_f32 v[94:95], v[160:161], v[94:95], v[66:67]
	v_cvt_pk_bf16_f32 v92, v92, v93
	v_pk_fma_f32 v[90:91], v[168:169], v[90:91], v[70:71]
	v_cvt_pk_bf16_f32 v93, v94, v95
	global_store_dwordx2 v[98:99], v[92:93], off
	v_cvt_pk_bf16_f32 v88, v88, v89
	v_cvt_pk_bf16_f32 v89, v90, v91
	global_store_dwordx2 v[98:99], v[88:89], off offset:32
	v_pk_fma_f32 v[86:87], v[172:173], v[86:87], v[74:75]
	v_cvt_pk_bf16_f32 v84, v84, v85
	v_pk_fma_f32 v[78:79], v[164:165], v[78:79], v[82:83]
	v_cvt_pk_bf16_f32 v85, v86, v87
	global_store_dwordx2 v[98:99], v[84:85], off offset:256
	v_cvt_pk_bf16_f32 v76, v76, v77
	v_cvt_pk_bf16_f32 v77, v78, v79
	global_store_dwordx2 v[98:99], v[76:77], off offset:288
	v_mov_b32_e32 v76, v219
	v_lshlrev_b64 v[78:79], 11, v[158:159]
	v_lshl_add_u64 v[78:79], v[178:179], 0, v[78:79]
	v_fmamk_f32 v76, v76, 0x3a800000, v197
	v_cmp_gt_f32_e32 vcc, s78, v76
	v_mul_f32_e32 v77, 0x4b800000, v76
	s_nop 0
	v_cndmask_b32_e32 v76, v76, v77, vcc
	v_rsq_f32_e32 v76, v76
	s_nop 0
	v_mul_f32_e32 v77, 0x45800000, v76
	v_cndmask_b32_e32 v76, v76, v77, vcc
	v_pk_mul_f32 v[60:61], v[60:61], v[76:77] op_sel_hi:[1,0]
	v_pk_mul_f32 v[56:57], v[56:57], v[76:77] op_sel_hi:[1,0]
	v_pk_mul_f32 v[52:53], v[52:53], v[76:77] op_sel_hi:[1,0]
	v_pk_mul_f32 v[48:49], v[48:49], v[76:77] op_sel_hi:[1,0]
	v_pk_mul_f32 v[62:63], v[62:63], v[76:77] op_sel_hi:[1,0]
	v_pk_fma_f32 v[60:61], v[162:163], v[60:61], v[64:65]
	v_pk_mul_f32 v[58:59], v[58:59], v[76:77] op_sel_hi:[1,0]
	v_pk_fma_f32 v[56:57], v[170:171], v[56:57], v[68:69]
	v_pk_mul_f32 v[54:55], v[54:55], v[76:77] op_sel_hi:[1,0]
	v_pk_fma_f32 v[52:53], v[174:175], v[52:53], v[72:73]
	v_pk_mul_f32 v[50:51], v[50:51], v[76:77] op_sel_hi:[1,0]
	v_pk_fma_f32 v[48:49], v[166:167], v[48:49], v[80:81]
; __device__ __forceinline__ unsigned pk2(float lo, float hi) { return pg8::cvt_pk_bf16(lo, hi); }
;     __device__ __forceinline__ void operator()(const f32x4 (&acc_)[2][2][4][2], const pg8::Unit& u, int wr, int wc, int fr, int fq) const {
;     ...
;             for (int ai = 0; ai < 2; ++ai)
; #pragma unroll
;                 for (int m = 0; m < 4; ++m) {
;                     const int row = row0 + ai * 128 + m * 16;
;                     const float rs = rsqrtf(__hip_atomic_load(rss + row, __ATOMIC_RELAXED, __HIP_MEMORY_SCOPE_AGENT) * (1.f / DM) + EPSN);
;                     const size_t off = (size_t)row * DM + col0;
; #pragma unroll
;                     for (int bj = 0; bj < 2; ++bj)
; #pragma unroll
;                         for (int n = 0; n < 2; ++n) { const f32x4 y = acc[ai][bj][m][n] * rs * gs[bj][n] + sh[bj][n];
;                             *(u32x2*)(xb + off + bj * 128 + n * 16) = (u32x2){pk2(y.x, y.y), pk2(y.z, y.w)}; }
;                 }
	v_pk_fma_f32 v[62:63], v[160:161], v[62:63], v[66:67]
	v_cvt_pk_bf16_f32 v60, v60, v61
	v_pk_fma_f32 v[58:59], v[168:169], v[58:59], v[70:71]
	v_cvt_pk_bf16_f32 v61, v62, v63
	global_store_dwordx2 v[78:79], v[60:61], off
	v_cvt_pk_bf16_f32 v56, v56, v57
	v_cvt_pk_bf16_f32 v57, v58, v59
	global_store_dwordx2 v[78:79], v[56:57], off offset:32
	v_pk_fma_f32 v[54:55], v[172:173], v[54:55], v[74:75]
	v_cvt_pk_bf16_f32 v52, v52, v53
	v_pk_fma_f32 v[50:51], v[164:165], v[50:51], v[82:83]
	v_cvt_pk_bf16_f32 v53, v54, v55
	global_store_dwordx2 v[78:79], v[52:53], off offset:256
	v_cvt_pk_bf16_f32 v48, v48, v49
	v_cvt_pk_bf16_f32 v49, v50, v51
	global_store_dwordx2 v[78:79], v[48:49], off offset:288
	v_mov_b32_e32 v48, v220
	v_lshlrev_b64 v[50:51], 11, v[156:157]
	v_lshl_add_u64 v[50:51], v[178:179], 0, v[50:51]
	v_fmamk_f32 v48, v48, 0x3a800000, v197
	v_cmp_gt_f32_e32 vcc, s78, v48
	v_mul_f32_e32 v49, 0x4b800000, v48
	s_nop 0
	v_cndmask_b32_e32 v48, v48, v49, vcc
	v_rsq_f32_e32 v48, v48
	s_nop 0
	v_mul_f32_e32 v49, 0x45800000, v48
	v_cndmask_b32_e32 v48, v48, v49, vcc
	v_pk_mul_f32 v[44:45], v[44:45], v[48:49] op_sel_hi:[1,0]
	v_pk_mul_f32 v[40:41], v[40:41], v[48:49] op_sel_hi:[1,0]
	v_pk_mul_f32 v[36:37], v[36:37], v[48:49] op_sel_hi:[1,0]
	v_pk_mul_f32 v[32:33], v[32:33], v[48:49] op_sel_hi:[1,0]
	v_pk_mul_f32 v[46:47], v[46:47], v[48:49] op_sel_hi:[1,0]
	v_pk_fma_f32 v[44:45], v[162:163], v[44:45], v[64:65]
	v_pk_mul_f32 v[42:43], v[42:43], v[48:49] op_sel_hi:[1,0]
	v_pk_fma_f32 v[40:41], v[170:171], v[40:41], v[68:69]
	v_pk_mul_f32 v[38:39], v[38:39], v[48:49] op_sel_hi:[1,0]
	v_pk_fma_f32 v[36:37], v[174:175], v[36:37], v[72:73]
	v_pk_mul_f32 v[34:35], v[34:35], v[48:49] op_sel_hi:[1,0]
	v_pk_fma_f32 v[32:33], v[166:167], v[32:33], v[80:81]
	v_pk_fma_f32 v[46:47], v[160:161], v[46:47], v[66:67]
	v_cvt_pk_bf16_f32 v44, v44, v45
	v_pk_fma_f32 v[42:43], v[168:169], v[42:43], v[70:71]
	v_cvt_pk_bf16_f32 v45, v46, v47
	global_store_dwordx2 v[50:51], v[44:45], off
	v_cvt_pk_bf16_f32 v40, v40, v41
	v_cvt_pk_bf16_f32 v41, v42, v43
	global_store_dwordx2 v[50:51], v[40:41], off offset:32
	v_pk_fma_f32 v[38:39], v[172:173], v[38:39], v[74:75]
	v_cvt_pk_bf16_f32 v36, v36, v37
	v_pk_fma_f32 v[34:35], v[164:165], v[34:35], v[82:83]
	v_cvt_pk_bf16_f32 v37, v38, v39
	global_store_dwordx2 v[50:51], v[36:37], off offset:256
	v_cvt_pk_bf16_f32 v32, v32, v33
	v_cvt_pk_bf16_f32 v33, v34, v35
	global_store_dwordx2 v[50:51], v[32:33], off offset:288
	v_mov_b32_e32 v32, v221
	v_lshlrev_b64 v[34:35], 11, v[154:155]
	v_lshl_add_u64 v[34:35], v[178:179], 0, v[34:35]
	v_fmamk_f32 v32, v32, 0x3a800000, v197
	v_cmp_gt_f32_e32 vcc, s78, v32
	v_mul_f32_e32 v33, 0x4b800000, v32
	s_nop 0
	v_cndmask_b32_e32 v32, v32, v33, vcc
	v_rsq_f32_e32 v32, v32
	s_nop 0
	v_mul_f32_e32 v33, 0x45800000, v32
	v_cndmask_b32_e32 v32, v32, v33, vcc
	v_pk_mul_f32 v[28:29], v[28:29], v[32:33] op_sel_hi:[1,0]
	v_pk_mul_f32 v[24:25], v[24:25], v[32:33] op_sel_hi:[1,0]
	v_pk_mul_f32 v[20:21], v[20:21], v[32:33] op_sel_hi:[1,0]
	v_pk_mul_f32 v[16:17], v[16:17], v[32:33] op_sel_hi:[1,0]
	v_pk_mul_f32 v[30:31], v[30:31], v[32:33] op_sel_hi:[1,0]
	v_pk_fma_f32 v[28:29], v[162:163], v[28:29], v[64:65]
	v_pk_mul_f32 v[26:27], v[26:27], v[32:33] op_sel_hi:[1,0]
	v_pk_fma_f32 v[24:25], v[170:171], v[24:25], v[68:69]
	v_pk_mul_f32 v[22:23], v[22:23], v[32:33] op_sel_hi:[1,0]
	v_pk_fma_f32 v[20:21], v[174:175], v[20:21], v[72:73]
	v_pk_mul_f32 v[18:19], v[18:19], v[32:33] op_sel_hi:[1,0]
	v_pk_fma_f32 v[16:17], v[166:167], v[16:17], v[80:81]
	v_pk_fma_f32 v[30:31], v[160:161], v[30:31], v[66:67]
	v_cvt_pk_bf16_f32 v28, v28, v29
	v_pk_fma_f32 v[26:27], v[168:169], v[26:27], v[70:71]
	v_cvt_pk_bf16_f32 v29, v30, v31
	global_store_dwordx2 v[34:35], v[28:29], off
	v_cvt_pk_bf16_f32 v24, v24, v25
	v_cvt_pk_bf16_f32 v25, v26, v27
	global_store_dwordx2 v[34:35], v[24:25], off offset:32
	v_pk_fma_f32 v[22:23], v[172:173], v[22:23], v[74:75]
	v_cvt_pk_bf16_f32 v20, v20, v21
	v_pk_fma_f32 v[18:19], v[164:165], v[18:19], v[82:83]
	v_cvt_pk_bf16_f32 v21, v22, v23
	global_store_dwordx2 v[34:35], v[20:21], off offset:256
	v_cvt_pk_bf16_f32 v16, v16, v17
	v_cvt_pk_bf16_f32 v17, v18, v19
	global_store_dwordx2 v[34:35], v[16:17], off offset:288
	v_mov_b32_e32 v16, v222
	v_lshlrev_b64 v[18:19], 11, v[152:153]
	v_lshl_add_u64 v[18:19], v[178:179], 0, v[18:19]
	v_fmamk_f32 v16, v16, 0x3a800000, v197
	v_cmp_gt_f32_e32 vcc, s78, v16
	v_mul_f32_e32 v17, 0x4b800000, v16
	s_nop 0
	v_cndmask_b32_e32 v16, v16, v17, vcc
	v_rsq_f32_e32 v16, v16
	s_nop 0
	v_mul_f32_e32 v17, 0x45800000, v16
	v_cndmask_b32_e32 v16, v16, v17, vcc
	v_pk_mul_f32 v[12:13], v[12:13], v[16:17] op_sel_hi:[1,0]
	v_pk_mul_f32 v[8:9], v[8:9], v[16:17] op_sel_hi:[1,0]
	v_pk_mul_f32 v[4:5], v[4:5], v[16:17] op_sel_hi:[1,0]
	v_pk_mul_f32 v[0:1], v[0:1], v[16:17] op_sel_hi:[1,0]
	v_pk_mul_f32 v[14:15], v[14:15], v[16:17] op_sel_hi:[1,0]
	v_pk_fma_f32 v[12:13], v[162:163], v[12:13], v[64:65]
	v_pk_mul_f32 v[10:11], v[10:11], v[16:17] op_sel_hi:[1,0]
	v_pk_fma_f32 v[8:9], v[170:171], v[8:9], v[68:69]
	v_pk_mul_f32 v[6:7], v[6:7], v[16:17] op_sel_hi:[1,0]
	v_pk_fma_f32 v[4:5], v[174:175], v[4:5], v[72:73]
	v_pk_mul_f32 v[2:3], v[2:3], v[16:17] op_sel_hi:[1,0]
	v_pk_fma_f32 v[0:1], v[166:167], v[0:1], v[80:81]
	v_pk_fma_f32 v[14:15], v[160:161], v[14:15], v[66:67]
	v_cvt_pk_bf16_f32 v12, v12, v13
	v_pk_fma_f32 v[10:11], v[168:169], v[10:11], v[70:71]
	v_cvt_pk_bf16_f32 v13, v14, v15
	global_store_dwordx2 v[18:19], v[12:13], off
	v_cvt_pk_bf16_f32 v8, v8, v9
	v_cvt_pk_bf16_f32 v9, v10, v11
	global_store_dwordx2 v[18:19], v[8:9], off offset:32
	v_pk_fma_f32 v[6:7], v[172:173], v[6:7], v[74:75]
	v_cvt_pk_bf16_f32 v4, v4, v5
	v_pk_fma_f32 v[2:3], v[164:165], v[2:3], v[82:83]
	v_cvt_pk_bf16_f32 v5, v6, v7
	global_store_dwordx2 v[18:19], v[4:5], off offset:256
	v_cvt_pk_bf16_f32 v0, v0, v1
	v_cvt_pk_bf16_f32 v1, v2, v3
	global_store_dwordx2 v[18:19], v[0:1], off offset:288
